# weight conversion re-split: P0 keeps layer-0 in/out only, layer-0 P2 slot converts L0 up/down + L1 in/out, layer-1 P2 idle slot converts L1 up/down; P0 rows 12/4
# speedup vs baseline: 1.0410x; 1.0020x over previous
.LBB0_24:
	v_writelane_b32 v253, s36, 42
	s_nop 1
	v_writelane_b32 v253, s37, 43
	v_writelane_b32 v253, s34, 44
	s_nop 1
	v_writelane_b32 v253, s35, 45
	s_or_b64 exec, exec, s[4:5]
	s_load_dwordx16 s[12:27], s[0:1], 0x0
	s_lshl_b32 s38, s78, 3
	s_waitcnt lgkmcnt(0)
	v_writelane_b32 v253, s12, 26
	s_nop 1
	v_writelane_b32 v253, s13, 27
	v_writelane_b32 v253, s14, 28
	v_writelane_b32 v253, s15, 29
	v_writelane_b32 v253, s16, 30
	v_writelane_b32 v253, s17, 31
	v_writelane_b32 v253, s18, 32
	v_writelane_b32 v253, s19, 33
	v_writelane_b32 v253, s20, 34
	v_writelane_b32 v253, s21, 35
	v_writelane_b32 v253, s22, 36
	v_writelane_b32 v253, s23, 37
	v_writelane_b32 v253, s24, 38
	v_writelane_b32 v253, s25, 39
	v_writelane_b32 v253, s26, 40
	v_writelane_b32 v253, s27, 41
	s_load_dwordx16 s[12:27], s[0:1], 0x40
	s_lshr_b32 s0, s8, 6
	s_lshl_b32 s1, s2, 3
	s_add_i32 s36, s0, s1
	s_waitcnt lgkmcnt(0)
	v_writelane_b32 v253, s12, 10
	s_nop 1
	v_writelane_b32 v253, s13, 11
	v_writelane_b32 v253, s14, 12
	v_writelane_b32 v253, s15, 13
	v_writelane_b32 v253, s16, 14
	v_writelane_b32 v253, s17, 15
	v_writelane_b32 v253, s18, 16
	v_writelane_b32 v253, s19, 17
	v_writelane_b32 v253, s20, 18
	v_writelane_b32 v253, s21, 19
	v_writelane_b32 v253, s22, 20
	v_writelane_b32 v253, s23, 21
	v_writelane_b32 v253, s24, 22
	v_writelane_b32 v253, s25, 23
	v_writelane_b32 v253, s26, 24
	v_writelane_b32 v253, s27, 25
	s_nop 0
	v_readlane_b32 s8, v253, 0
	v_readlane_b32 s10, v253, 2
	v_readlane_b32 s11, v253, 3
	s_add_u32 s64, s10, 0x400000
	s_addc_u32 s65, s11, 0
	s_cmpk_gt_i32 s36, 0x2fff
	v_readlane_b32 s9, v253, 1
	s_cbranch_scc1 .LBB0_178
	v_and_b32_e32 v219, 31, v227
	v_lshlrev_b32_e32 v212, 4, v219
	v_lshrrev_b32_e32 v213, 5, v227
	v_lshlrev_b32_e32 v214, 2, v219
	v_and_b32_e32 v215, 64, v214
	v_add_u32_e32 v215, v215, v214
	v_lshlrev_b32_e32 v216, 5, v213
	v_readlane_b32 s8, v253, 36
	v_readlane_b32 s9, v253, 37
	v_readlane_b32 s10, v253, 34
	v_readlane_b32 s11, v253, 35
	v_readlane_b32 s12, v253, 16
	v_readlane_b32 s13, v253, 17
	v_readlane_b32 s14, v253, 18
	v_readlane_b32 s15, v253, 19
	v_readlane_b32 s16, v253, 20
	v_readlane_b32 s17, v253, 21
	v_readlane_b32 s18, v253, 22
	v_readlane_b32 s19, v253, 23
	s_mov_b32 s66, s36
	s_movk_i32 s98, 0x17ff
	s_mov_b32 s99, s38
	s_cmpk_eq_u32 s78, 0x100
	s_cbranch_scc0 .Lwt_loop
	s_movk_i32 s98, 0x3ff
	s_movk_i32 s99, 0x400
	s_cmpk_lt_u32 s66, 0x400
	s_cbranch_scc1 .Lwt_loop
	s_movk_i32 s66, 0x7fff

.Lwt_done:
.LBB0_178:
	v_readlane_b32 s8, v253, 0
	v_readlane_b32 s10, v253, 2
	v_readlane_b32 s11, v253, 3
	s_add_u32 s46, s10, 0x3400000
	s_addc_u32 s47, s11, 0
	s_cmpk_lt_i32 s36, 0x4200
	s_cselect_b64 s[0:1], -1, 0
	v_readlane_b32 s9, v253, 1
	v_writelane_b32 v253, s0, 46
	s_cmpk_gt_i32 s36, 0x41ff
	v_mbcnt_lo_u32_b32 v42, -1, 0
	v_writelane_b32 v253, s1, 47
	s_cbranch_scc1 .LBB0_192
	v_mbcnt_hi_u32_b32 v3, -1, v42
	s_ashr_i32 s39, s38, 31
	v_lshlrev_b32_e32 v4, 4, v227
	v_lshlrev_b32_e32 v5, 3, v227
	v_mov_b32_e32 v12, 0
	v_xor_b32_e32 v6, 1, v227
	v_lshlrev_b32_e32 v6, 2, v6
	v_xor_b32_e32 v7, 2, v227
	v_lshlrev_b32_e32 v7, 2, v7
	v_xor_b32_e32 v8, 4, v227
	v_lshlrev_b32_e32 v8, 2, v8
	v_xor_b32_e32 v9, 8, v227
	v_lshlrev_b32_e32 v9, 2, v9
	v_xor_b32_e32 v10, 16, v227
	v_lshlrev_b32_e32 v10, 2, v10
	v_xor_b32_e32 v11, 32, v227
	v_lshlrev_b32_e32 v11, 2, v11
	v_readlane_b32 s48, v253, 26
	v_readlane_b32 s49, v253, 27
	v_readlane_b32 s50, v253, 28
	v_readlane_b32 s51, v253, 29
	v_readlane_b32 s52, v253, 44
	v_readlane_b32 s53, v253, 45
	s_mov_b32 s14, s36
	s_movk_i32 s98, 0x4200
	s_mov_b32 s99, s38
	s_cmpk_eq_u32 s78, 0x100
	s_cbranch_scc0 .Lxn_loop
	s_movk_i32 s99, 0x400
	s_cmpk_lt_u32 s36, 0x400
	s_cbranch_scc1 .Lxn_low
	s_add_i32 s14, s36, 0xfffffc00
	s_movk_i32 s98, 0x3000
	s_branch .Lxn_loop
.Lxn_low:
	s_add_i32 s14, s36, 0x3000

.LBB0_441:
	s_or_b64 exec, exec, s[40:41]
	s_xor_b64 s[0:1], s[62:63], -1
	v_writelane_b32 v252, s0, 48
	s_mov_b32 s37, s93
	s_andn2_b64 vcc, exec, s[66:67]
	v_writelane_b32 v252, s1, 49
	s_waitcnt lgkmcnt(0)
	s_barrier
	s_cbranch_vccnz .LBB0_531
	v_readlane_b32 s98, v252, 47
	s_cmp_lg_u32 s98, 0
	s_cbranch_scc1 .Lw1b_skip
	s_cmpk_lg_u32 s78, 0x100
	s_cbranch_scc1 .Lw1b_skip
	s_cmpk_lt_u32 s2, 0x80
	s_cbranch_scc1 .Lw1b_skip
	v_writelane_b32 v254, s8, 0
	v_writelane_b32 v254, s9, 1
	v_writelane_b32 v254, s10, 2
	v_writelane_b32 v254, s11, 3
	v_writelane_b32 v254, s12, 4
	v_writelane_b32 v254, s13, 5
	v_writelane_b32 v254, s14, 6
	v_writelane_b32 v254, s15, 7
	v_writelane_b32 v254, s16, 8
	v_writelane_b32 v254, s17, 9
	v_writelane_b32 v254, s18, 10
	v_writelane_b32 v254, s19, 11
	v_writelane_b32 v254, s20, 12
	v_writelane_b32 v254, s21, 13
	v_writelane_b32 v254, s22, 14
	v_writelane_b32 v254, s23, 15
	v_writelane_b32 v254, s24, 16
	v_writelane_b32 v254, s25, 17
	v_writelane_b32 v254, s26, 18
	v_writelane_b32 v254, s27, 19
	v_writelane_b32 v254, s28, 20
	v_writelane_b32 v254, s29, 21
	v_writelane_b32 v254, s30, 22
	v_writelane_b32 v254, s31, 23
	v_writelane_b32 v254, s32, 24
	v_writelane_b32 v254, s33, 25
	v_writelane_b32 v254, s34, 26
	v_writelane_b32 v254, s35, 27
	v_writelane_b32 v254, s40, 28
	v_writelane_b32 v254, s41, 29
	v_writelane_b32 v254, s42, 30
	v_writelane_b32 v254, s43, 31
	v_writelane_b32 v254, s44, 32
	v_writelane_b32 v254, s45, 33
	v_writelane_b32 v254, s46, 34
	v_writelane_b32 v254, s47, 35
	v_writelane_b32 v254, s48, 36
	v_writelane_b32 v254, s49, 37
	v_writelane_b32 v254, s50, 38
	v_writelane_b32 v254, s51, 39
	v_writelane_b32 v254, s52, 40
	v_writelane_b32 v254, s53, 41
	v_writelane_b32 v254, s54, 42
	v_writelane_b32 v254, s55, 43
	v_writelane_b32 v254, s56, 44
	v_writelane_b32 v254, s57, 45
	v_writelane_b32 v254, s58, 46
	v_writelane_b32 v254, s59, 47
	v_writelane_b32 v254, s60, 48
	v_writelane_b32 v254, s61, 49
	v_writelane_b32 v254, s62, 50
	v_writelane_b32 v254, s63, 51
	v_writelane_b32 v254, s66, 52
	v_writelane_b32 v254, s67, 53
	v_writelane_b32 v254, s68, 54
	v_writelane_b32 v254, s69, 55
	v_writelane_b32 v254, s70, 56
	v_writelane_b32 v254, s71, 57
	v_writelane_b32 v254, s72, 58
	v_writelane_b32 v254, s73, 59
	v_writelane_b32 v254, s74, 60
	v_writelane_b32 v254, s75, 61
	v_writelane_b32 v254, s76, 62
	v_writelane_b32 v254, s77, 63
	v_writelane_b32 v255, s80, 0
	v_writelane_b32 v255, s81, 1
	v_writelane_b32 v255, s82, 2
	v_writelane_b32 v255, s83, 3
	v_writelane_b32 v255, s84, 4
	v_writelane_b32 v255, s85, 5
	v_writelane_b32 v255, s86, 6
	v_writelane_b32 v255, s87, 7
	v_writelane_b32 v255, s88, 8
	v_writelane_b32 v255, s89, 9
	v_writelane_b32 v255, s90, 10
	v_writelane_b32 v255, s91, 11
	v_writelane_b32 v255, s92, 12
	v_writelane_b32 v255, s93, 13
	v_writelane_b32 v255, s94, 14
	v_writelane_b32 v255, s95, 15
	v_writelane_b32 v255, s4, 16
	v_writelane_b32 v255, s5, 17
	v_writelane_b32 v255, s0, 18
	v_writelane_b32 v255, s1, 19
	v_and_b32_e32 v207, 31, v227
	v_lshlrev_b32_e32 v200, 4, v207
	v_lshrrev_b32_e32 v201, 5, v227
	v_lshlrev_b32_e32 v202, 2, v207
	v_and_b32_e32 v203, 64, v202
	v_add_u32_e32 v203, v203, v202
	v_lshlrev_b32_e32 v204, 5, v201
	v_readlane_b32 s8, v253, 36
	v_readlane_b32 s9, v253, 37
	v_readlane_b32 s10, v253, 34
	v_readlane_b32 s11, v253, 35
	v_readlane_b32 s12, v253, 16
	v_readlane_b32 s13, v253, 17
	v_readlane_b32 s14, v253, 18
	v_readlane_b32 s15, v253, 19
	v_readlane_b32 s16, v253, 20
	v_readlane_b32 s17, v253, 21
	v_readlane_b32 s18, v253, 22
	v_readlane_b32 s19, v253, 23
	v_readfirstlane_b32 s66, v226
	s_lshr_b32 s66, s66, 6
	s_add_i32 s67, s2, 0xffffff80
	s_lshl_b32 s67, s67, 3
	s_add_i32 s66, s66, s67
	s_addk_i32 s66, 0x400
	s_add_i32 s68, s66, 0x400
	s_add_i32 s67, s66, 0x800
	s_cmpk_ge_i32 s66, 0xc00
	s_cselect_b32 s0, 1, 0
	s_mul_i32 s1, s0, 0xc00
	s_sub_i32 s1, s66, s1
	s_mul_i32 s4, s0, 0x1800000
	s_add_u32 s70, s64, s4
	s_addc_u32 s71, s65, 0
	s_lshl_b32 s69, s0, 12
	s_cmpk_lt_i32 s1, 0x300
	s_cbranch_scc1 .Lw1b_in_7
	s_cmpk_lt_i32 s1, 0x400
	s_cbranch_scc1 .Lw1b_out_7
	s_cmpk_lt_i32 s1, 0x800
	s_cbranch_scc1 .Lw1b_up_7
	s_sub_i32 s1, s1, 0x800
	s_and_b32 s75, s1, 1
	s_lshr_b32 s1, s1, 1
	s_lshr_b32 s72, s1, 3
	s_and_b32 s73, s1, 7
	s_lshl_b32 s72, s72, 1
	s_or_b32 s72, s72, s75
	s_movk_i32 s74, 0x400
	s_mul_i32 s4, s0, 0x1000000
	s_add_u32 s76, s18, s4
	s_addc_u32 s77, s19, 0
	s_mov_b32 s4, 0x1000000
	s_lshl_b32 s5, s73, 7
	s_movk_i32 s27, 0xd00
	s_branch .Lw1b_join_7

.Lw1b_nomul_12:
	v_cvt_pk_bf16_f32 v236, v136, v140
	v_cvt_pk_bf16_f32 v237, v144, v148
	v_cvt_pk_bf16_f32 v238, v152, v156
	v_cvt_pk_bf16_f32 v239, v160, v164
	global_store_dwordx4 v206, v[236:239], s[42:43]
	v_cvt_pk_bf16_f32 v240, v168, v172
	v_cvt_pk_bf16_f32 v241, v176, v180
	v_cvt_pk_bf16_f32 v242, v184, v188
	v_cvt_pk_bf16_f32 v243, v192, v196
	global_store_dwordx4 v206, v[240:243], s[42:43] offset:16
	s_add_u32 s42, s42, s4
	s_addc_u32 s43, s43, 0
	v_cvt_pk_bf16_f32 v244, v137, v141
	v_cvt_pk_bf16_f32 v245, v145, v149
	v_cvt_pk_bf16_f32 v246, v153, v157
	v_cvt_pk_bf16_f32 v247, v161, v165
	global_store_dwordx4 v206, v[244:247], s[42:43]
	v_cvt_pk_bf16_f32 v248, v169, v173
	v_cvt_pk_bf16_f32 v249, v177, v181
	v_cvt_pk_bf16_f32 v250, v185, v189
	v_cvt_pk_bf16_f32 v251, v193, v197
	global_store_dwordx4 v206, v[248:251], s[42:43] offset:16
	s_add_u32 s42, s42, s4
	s_addc_u32 s43, s43, 0
	v_cvt_pk_bf16_f32 v236, v138, v142
	v_cvt_pk_bf16_f32 v237, v146, v150
	v_cvt_pk_bf16_f32 v238, v154, v158
	v_cvt_pk_bf16_f32 v239, v162, v166
	global_store_dwordx4 v206, v[236:239], s[42:43]
	v_cvt_pk_bf16_f32 v240, v170, v174
	v_cvt_pk_bf16_f32 v241, v178, v182
	v_cvt_pk_bf16_f32 v242, v186, v190
	v_cvt_pk_bf16_f32 v243, v194, v198
	global_store_dwordx4 v206, v[240:243], s[42:43] offset:16
	s_add_u32 s42, s42, s4
	s_addc_u32 s43, s43, 0
	v_cvt_pk_bf16_f32 v244, v139, v143
	v_cvt_pk_bf16_f32 v245, v147, v151
	v_cvt_pk_bf16_f32 v246, v155, v159
	v_cvt_pk_bf16_f32 v247, v163, v167
	global_store_dwordx4 v206, v[244:247], s[42:43]
	v_cvt_pk_bf16_f32 v248, v171, v175
	v_cvt_pk_bf16_f32 v249, v179, v183
	v_cvt_pk_bf16_f32 v250, v187, v191
	v_cvt_pk_bf16_f32 v251, v195, v199
	global_store_dwordx4 v206, v[248:251], s[42:43] offset:16
	v_readlane_b32 s8, v254, 0
	v_readlane_b32 s9, v254, 1
	v_readlane_b32 s10, v254, 2
	v_readlane_b32 s11, v254, 3
	v_readlane_b32 s12, v254, 4
	v_readlane_b32 s13, v254, 5
	v_readlane_b32 s14, v254, 6
	v_readlane_b32 s15, v254, 7
	v_readlane_b32 s16, v254, 8
	v_readlane_b32 s17, v254, 9
	v_readlane_b32 s18, v254, 10
	v_readlane_b32 s19, v254, 11
	v_readlane_b32 s20, v254, 12
	v_readlane_b32 s21, v254, 13
	v_readlane_b32 s22, v254, 14
	v_readlane_b32 s23, v254, 15
	v_readlane_b32 s24, v254, 16
	v_readlane_b32 s25, v254, 17
	v_readlane_b32 s26, v254, 18
	v_readlane_b32 s27, v254, 19
	v_readlane_b32 s28, v254, 20
	v_readlane_b32 s29, v254, 21
	v_readlane_b32 s30, v254, 22
	v_readlane_b32 s31, v254, 23
	v_readlane_b32 s32, v254, 24
	v_readlane_b32 s33, v254, 25
	v_readlane_b32 s34, v254, 26
	v_readlane_b32 s35, v254, 27
	v_readlane_b32 s40, v254, 28
	v_readlane_b32 s41, v254, 29
	v_readlane_b32 s42, v254, 30
	v_readlane_b32 s43, v254, 31
	v_readlane_b32 s44, v254, 32
	v_readlane_b32 s45, v254, 33
	v_readlane_b32 s46, v254, 34
	v_readlane_b32 s47, v254, 35
	v_readlane_b32 s48, v254, 36
	v_readlane_b32 s49, v254, 37
	v_readlane_b32 s50, v254, 38
	v_readlane_b32 s51, v254, 39
	v_readlane_b32 s52, v254, 40
	v_readlane_b32 s53, v254, 41
	v_readlane_b32 s54, v254, 42
	v_readlane_b32 s55, v254, 43
	v_readlane_b32 s56, v254, 44
	v_readlane_b32 s57, v254, 45
	v_readlane_b32 s58, v254, 46
	v_readlane_b32 s59, v254, 47
	v_readlane_b32 s60, v254, 48
	v_readlane_b32 s61, v254, 49
	v_readlane_b32 s62, v254, 50
	v_readlane_b32 s63, v254, 51
	v_readlane_b32 s66, v254, 52
	v_readlane_b32 s67, v254, 53
	v_readlane_b32 s68, v254, 54
	v_readlane_b32 s69, v254, 55
	v_readlane_b32 s70, v254, 56
	v_readlane_b32 s71, v254, 57
	v_readlane_b32 s72, v254, 58
	v_readlane_b32 s73, v254, 59
	v_readlane_b32 s74, v254, 60
	v_readlane_b32 s75, v254, 61
	v_readlane_b32 s76, v254, 62
	v_readlane_b32 s77, v254, 63
	v_readlane_b32 s80, v255, 0
	v_readlane_b32 s81, v255, 1
	v_readlane_b32 s82, v255, 2
	v_readlane_b32 s83, v255, 3
	v_readlane_b32 s84, v255, 4
	v_readlane_b32 s85, v255, 5
	v_readlane_b32 s86, v255, 6
	v_readlane_b32 s87, v255, 7
	v_readlane_b32 s88, v255, 8
	v_readlane_b32 s89, v255, 9
	v_readlane_b32 s90, v255, 10
	v_readlane_b32 s91, v255, 11
	v_readlane_b32 s92, v255, 12
	v_readlane_b32 s93, v255, 13
	v_readlane_b32 s94, v255, 14
	v_readlane_b32 s95, v255, 15
	v_readlane_b32 s4, v255, 16
	v_readlane_b32 s5, v255, 17
	v_readlane_b32 s0, v255, 18
	v_readlane_b32 s1, v255, 19
.Lw1b_skip:
	v_readlane_b32 s98, v252, 47
	s_cmp_eq_u32 s98, 0
	s_cbranch_scc1 .Lw1c_skip
	s_cmpk_lg_u32 s78, 0x100
	s_cbranch_scc1 .Lw1c_skip
	s_cmpk_lt_u32 s2, 0x80
	s_cbranch_scc1 .Lw1c_skip
	v_writelane_b32 v254, s8, 0
	v_writelane_b32 v254, s9, 1
	v_writelane_b32 v254, s10, 2
	v_writelane_b32 v254, s11, 3
	v_writelane_b32 v254, s12, 4
	v_writelane_b32 v254, s13, 5
	v_writelane_b32 v254, s14, 6
	v_writelane_b32 v254, s15, 7
	v_writelane_b32 v254, s16, 8
	v_writelane_b32 v254, s17, 9
	v_writelane_b32 v254, s18, 10
	v_writelane_b32 v254, s19, 11
	v_writelane_b32 v254, s20, 12
	v_writelane_b32 v254, s21, 13
	v_writelane_b32 v254, s22, 14
	v_writelane_b32 v254, s23, 15
	v_writelane_b32 v254, s24, 16
	v_writelane_b32 v254, s25, 17
	v_writelane_b32 v254, s26, 18
	v_writelane_b32 v254, s27, 19
	v_writelane_b32 v254, s28, 20
	v_writelane_b32 v254, s29, 21
	v_writelane_b32 v254, s30, 22
	v_writelane_b32 v254, s31, 23
	v_writelane_b32 v254, s32, 24
	v_writelane_b32 v254, s33, 25
	v_writelane_b32 v254, s34, 26
	v_writelane_b32 v254, s35, 27
	v_writelane_b32 v254, s40, 28
	v_writelane_b32 v254, s41, 29
	v_writelane_b32 v254, s42, 30
	v_writelane_b32 v254, s43, 31
	v_writelane_b32 v254, s44, 32
	v_writelane_b32 v254, s45, 33
	v_writelane_b32 v254, s46, 34
	v_writelane_b32 v254, s47, 35
	v_writelane_b32 v254, s48, 36
	v_writelane_b32 v254, s49, 37
	v_writelane_b32 v254, s50, 38
	v_writelane_b32 v254, s51, 39
	v_writelane_b32 v254, s52, 40
	v_writelane_b32 v254, s53, 41
	v_writelane_b32 v254, s54, 42
	v_writelane_b32 v254, s55, 43
	v_writelane_b32 v254, s56, 44
	v_writelane_b32 v254, s57, 45
	v_writelane_b32 v254, s58, 46
	v_writelane_b32 v254, s59, 47
	v_writelane_b32 v254, s60, 48
	v_writelane_b32 v254, s61, 49
	v_writelane_b32 v254, s62, 50
	v_writelane_b32 v254, s63, 51
	v_writelane_b32 v254, s66, 52
	v_writelane_b32 v254, s67, 53
	v_writelane_b32 v254, s68, 54
	v_writelane_b32 v254, s69, 55
	v_writelane_b32 v254, s70, 56
	v_writelane_b32 v254, s71, 57
	v_writelane_b32 v254, s72, 58
	v_writelane_b32 v254, s73, 59
	v_writelane_b32 v254, s74, 60
	v_writelane_b32 v254, s75, 61
	v_writelane_b32 v254, s76, 62
	v_writelane_b32 v254, s77, 63
	v_writelane_b32 v255, s80, 0
	v_writelane_b32 v255, s81, 1
	v_writelane_b32 v255, s82, 2
	v_writelane_b32 v255, s83, 3
	v_writelane_b32 v255, s84, 4
	v_writelane_b32 v255, s85, 5
	v_writelane_b32 v255, s86, 6
	v_writelane_b32 v255, s87, 7
	v_writelane_b32 v255, s88, 8
	v_writelane_b32 v255, s89, 9
	v_writelane_b32 v255, s90, 10
	v_writelane_b32 v255, s91, 11
	v_writelane_b32 v255, s92, 12
	v_writelane_b32 v255, s93, 13
	v_writelane_b32 v255, s94, 14
	v_writelane_b32 v255, s95, 15
	v_writelane_b32 v255, s4, 16
	v_writelane_b32 v255, s5, 17
	v_writelane_b32 v255, s0, 18
	v_writelane_b32 v255, s1, 19
	v_and_b32_e32 v207, 31, v227
	v_lshlrev_b32_e32 v200, 4, v207
	v_lshrrev_b32_e32 v201, 5, v227
	v_lshlrev_b32_e32 v202, 2, v207
	v_and_b32_e32 v203, 64, v202
	v_add_u32_e32 v203, v203, v202
	v_lshlrev_b32_e32 v204, 5, v201
	v_readlane_b32 s8, v253, 36
	v_readlane_b32 s9, v253, 37
	v_readlane_b32 s10, v253, 34
	v_readlane_b32 s11, v253, 35
	v_readlane_b32 s12, v253, 16
	v_readlane_b32 s13, v253, 17
	v_readlane_b32 s14, v253, 18
	v_readlane_b32 s15, v253, 19
	v_readlane_b32 s16, v253, 20
	v_readlane_b32 s17, v253, 21
	v_readlane_b32 s18, v253, 22
	v_readlane_b32 s19, v253, 23
	v_readfirstlane_b32 s66, v226
	s_lshr_b32 s66, s66, 6
	s_add_i32 s67, s2, 0xffffff80
	s_lshl_b32 s67, s67, 3
	s_add_i32 s66, s66, s67
	s_addk_i32 s66, 0x1000
	s_add_i32 s68, s66, 0x400
	s_cmpk_ge_i32 s66, 0xc00
	s_cselect_b32 s0, 1, 0
	s_mul_i32 s1, s0, 0xc00
	s_sub_i32 s1, s66, s1
	s_mul_i32 s4, s0, 0x1800000
	s_add_u32 s70, s64, s4
	s_addc_u32 s71, s65, 0
	s_lshl_b32 s69, s0, 12
	s_cmpk_lt_i32 s1, 0x300
	s_cbranch_scc1 .Lw1c_in_13
	s_cmpk_lt_i32 s1, 0x400
	s_cbranch_scc1 .Lw1c_out_13
	s_cmpk_lt_i32 s1, 0x800
	s_cbranch_scc1 .Lw1c_up_13
	s_sub_i32 s1, s1, 0x800
	s_and_b32 s75, s1, 1
	s_lshr_b32 s1, s1, 1
	s_lshr_b32 s72, s1, 3
	s_and_b32 s73, s1, 7
	s_lshl_b32 s72, s72, 1
	s_or_b32 s72, s72, s75
	s_movk_i32 s74, 0x400
	s_mul_i32 s4, s0, 0x1000000
	s_add_u32 s76, s18, s4
	s_addc_u32 s77, s19, 0
	s_mov_b32 s4, 0x1000000
	s_lshl_b32 s5, s73, 7
	s_movk_i32 s27, 0xd00
	s_branch .Lw1c_join_13

.Lw1c_join_14:
	s_mul_i32 s0, s72, s74
	s_lshl_b32 s0, s0, 5
	s_lshl_b32 s1, s73, 7
	s_add_i32 s0, s0, s1
	s_lshl_b32 s0, s0, 2
	s_add_u32 s28, s76, s0
	s_addc_u32 s29, s77, 0
	s_lshl_b32 s34, s74, 2
	s_lshr_b32 s0, s35, 8
	s_lshl_b32 s0, s5, s0
	s_add_i32 s0, s0, s4
	s_lshl_b32 s1, s72, 6
	s_add_i32 s0, s0, s1
	s_add_u32 s30, s70, s0
	s_addc_u32 s31, s71, 0
	s_lshl_b32 s1, s72, 7
	s_add_u32 s32, s32, s1
	s_addc_u32 s33, s33, 0
	s_lshl_b32 s0, s34, 4
	v_mad_u32_u24 v205, v201, s0, v200
	global_load_dwordx4 v[72:75], v205, s[28:29] nt
	s_add_u32 s28, s28, s34
	s_addc_u32 s29, s29, 0
	global_load_dwordx4 v[76:79], v205, s[28:29] nt
	s_add_u32 s28, s28, s34
	s_addc_u32 s29, s29, 0
	global_load_dwordx4 v[80:83], v205, s[28:29] nt
	s_add_u32 s28, s28, s34
	s_addc_u32 s29, s29, 0
	global_load_dwordx4 v[84:87], v205, s[28:29] nt
	s_add_u32 s28, s28, s34
	s_addc_u32 s29, s29, 0
	global_load_dwordx4 v[88:91], v205, s[28:29] nt
	s_add_u32 s28, s28, s34
	s_addc_u32 s29, s29, 0
	global_load_dwordx4 v[92:95], v205, s[28:29] nt
	s_add_u32 s28, s28, s34
	s_addc_u32 s29, s29, 0
	global_load_dwordx4 v[96:99], v205, s[28:29] nt
	s_add_u32 s28, s28, s34
	s_addc_u32 s29, s29, 0
	global_load_dwordx4 v[100:103], v205, s[28:29] nt
	s_add_u32 s28, s28, s34
	s_addc_u32 s29, s29, 0
	global_load_dwordx4 v[104:107], v205, s[28:29] nt
	s_add_u32 s28, s28, s34
	s_addc_u32 s29, s29, 0
	global_load_dwordx4 v[108:111], v205, s[28:29] nt
	s_add_u32 s28, s28, s34
	s_addc_u32 s29, s29, 0
	global_load_dwordx4 v[112:115], v205, s[28:29] nt
	s_add_u32 s28, s28, s34
	s_addc_u32 s29, s29, 0
	global_load_dwordx4 v[116:119], v205, s[28:29] nt
	s_add_u32 s28, s28, s34
	s_addc_u32 s29, s29, 0
	global_load_dwordx4 v[120:123], v205, s[28:29] nt
	s_add_u32 s28, s28, s34
	s_addc_u32 s29, s29, 0
	global_load_dwordx4 v[124:127], v205, s[28:29] nt
	s_add_u32 s28, s28, s34
	s_addc_u32 s29, s29, 0
	global_load_dwordx4 v[128:131], v205, s[28:29] nt
	s_add_u32 s28, s28, s34
	s_addc_u32 s29, s29, 0
	global_load_dwordx4 v[132:135], v205, s[28:29] nt
	s_bitcmp1_b32 s27, 0
	s_cbranch_scc0 .Lw1c_nog_15
	s_load_dwordx16 s[80:95], s[24:25], 0x0
	s_load_dwordx16 s[48:63], s[24:25], 0x40
.Lw1c_nog_15:
	s_bitcmp1_b32 s27, 1
	s_cselect_b64 vcc, -1, 0
	s_lshr_b32 s0, s27, 8
	s_lshl_b32 s4, 1, s0
	v_cndmask_b32_e32 v207, v202, v203, vcc
	v_lshlrev_b32_e32 v206, s0, v207
	v_add_u32_e32 v206, v206, v204
	s_waitcnt vmcnt(16)
	s_bitcmp1_b32 s27, 0
	s_cbranch_scc0 .Lw1c_nomul_15
	s_waitcnt lgkmcnt(0)
	s_mov_b32 exec_hi, 0
	v_mul_f32_e32 v8, s80, v8
	v_mul_f32_e32 v9, s80, v9
	v_mul_f32_e32 v10, s80, v10
	v_mul_f32_e32 v11, s80, v11
	v_mul_f32_e32 v12, s81, v12
	v_mul_f32_e32 v13, s81, v13
	v_mul_f32_e32 v14, s81, v14
	v_mul_f32_e32 v15, s81, v15
	v_mul_f32_e32 v16, s82, v16
	v_mul_f32_e32 v17, s82, v17
	v_mul_f32_e32 v18, s82, v18
	v_mul_f32_e32 v19, s82, v19
	v_mul_f32_e32 v20, s83, v20
	v_mul_f32_e32 v21, s83, v21
	v_mul_f32_e32 v22, s83, v22
	v_mul_f32_e32 v23, s83, v23
	v_mul_f32_e32 v24, s84, v24
	v_mul_f32_e32 v25, s84, v25
	v_mul_f32_e32 v26, s84, v26
	v_mul_f32_e32 v27, s84, v27
	v_mul_f32_e32 v28, s85, v28
	v_mul_f32_e32 v29, s85, v29
	v_mul_f32_e32 v30, s85, v30
	v_mul_f32_e32 v31, s85, v31
	v_mul_f32_e32 v32, s86, v32
	v_mul_f32_e32 v33, s86, v33
	v_mul_f32_e32 v34, s86, v34
	v_mul_f32_e32 v35, s86, v35
	v_mul_f32_e32 v36, s87, v36
	v_mul_f32_e32 v37, s87, v37
	v_mul_f32_e32 v38, s87, v38
	v_mul_f32_e32 v39, s87, v39
	v_mul_f32_e32 v40, s88, v40
	v_mul_f32_e32 v41, s88, v41
	v_mul_f32_e32 v42, s88, v42
	v_mul_f32_e32 v43, s88, v43
	v_mul_f32_e32 v44, s89, v44
	v_mul_f32_e32 v45, s89, v45
	v_mul_f32_e32 v46, s89, v46
	v_mul_f32_e32 v47, s89, v47
	v_mul_f32_e32 v48, s90, v48
	v_mul_f32_e32 v49, s90, v49
	v_mul_f32_e32 v50, s90, v50
	v_mul_f32_e32 v51, s90, v51
	v_mul_f32_e32 v52, s91, v52
	v_mul_f32_e32 v53, s91, v53
	v_mul_f32_e32 v54, s91, v54
	v_mul_f32_e32 v55, s91, v55
	v_mul_f32_e32 v56, s92, v56
	v_mul_f32_e32 v57, s92, v57
	v_mul_f32_e32 v58, s92, v58
	v_mul_f32_e32 v59, s92, v59
	v_mul_f32_e32 v60, s93, v60
	v_mul_f32_e32 v61, s93, v61
	v_mul_f32_e32 v62, s93, v62
	v_mul_f32_e32 v63, s93, v63
	v_mul_f32_e32 v64, s94, v64
	v_mul_f32_e32 v65, s94, v65
	v_mul_f32_e32 v66, s94, v66
	v_mul_f32_e32 v67, s94, v67
	v_mul_f32_e32 v68, s95, v68
	v_mul_f32_e32 v69, s95, v69
	v_mul_f32_e32 v70, s95, v70
	v_mul_f32_e32 v71, s95, v71
	s_mov_b32 exec_lo, 0
	s_mov_b32 exec_hi, -1
	v_mul_f32_e32 v8, s48, v8
	v_mul_f32_e32 v9, s48, v9
	v_mul_f32_e32 v10, s48, v10
	v_mul_f32_e32 v11, s48, v11
	v_mul_f32_e32 v12, s49, v12
	v_mul_f32_e32 v13, s49, v13
	v_mul_f32_e32 v14, s49, v14
	v_mul_f32_e32 v15, s49, v15
	v_mul_f32_e32 v16, s50, v16
	v_mul_f32_e32 v17, s50, v17
	v_mul_f32_e32 v18, s50, v18
	v_mul_f32_e32 v19, s50, v19
	v_mul_f32_e32 v20, s51, v20
	v_mul_f32_e32 v21, s51, v21
	v_mul_f32_e32 v22, s51, v22
	v_mul_f32_e32 v23, s51, v23
	v_mul_f32_e32 v24, s52, v24
	v_mul_f32_e32 v25, s52, v25
	v_mul_f32_e32 v26, s52, v26
	v_mul_f32_e32 v27, s52, v27
	v_mul_f32_e32 v28, s53, v28
	v_mul_f32_e32 v29, s53, v29
	v_mul_f32_e32 v30, s53, v30
	v_mul_f32_e32 v31, s53, v31
	v_mul_f32_e32 v32, s54, v32
	v_mul_f32_e32 v33, s54, v33
	v_mul_f32_e32 v34, s54, v34
	v_mul_f32_e32 v35, s54, v35
	v_mul_f32_e32 v36, s55, v36
	v_mul_f32_e32 v37, s55, v37
	v_mul_f32_e32 v38, s55, v38
	v_mul_f32_e32 v39, s55, v39
	v_mul_f32_e32 v40, s56, v40
	v_mul_f32_e32 v41, s56, v41
	v_mul_f32_e32 v42, s56, v42
	v_mul_f32_e32 v43, s56, v43
	v_mul_f32_e32 v44, s57, v44
	v_mul_f32_e32 v45, s57, v45
	v_mul_f32_e32 v46, s57, v46
	v_mul_f32_e32 v47, s57, v47
	v_mul_f32_e32 v48, s58, v48
	v_mul_f32_e32 v49, s58, v49
	v_mul_f32_e32 v50, s58, v50
	v_mul_f32_e32 v51, s58, v51
	v_mul_f32_e32 v52, s59, v52
	v_mul_f32_e32 v53, s59, v53
	v_mul_f32_e32 v54, s59, v54
	v_mul_f32_e32 v55, s59, v55
	v_mul_f32_e32 v56, s60, v56
	v_mul_f32_e32 v57, s60, v57
	v_mul_f32_e32 v58, s60, v58
	v_mul_f32_e32 v59, s60, v59
	v_mul_f32_e32 v60, s61, v60
	v_mul_f32_e32 v61, s61, v61
	v_mul_f32_e32 v62, s61, v62
	v_mul_f32_e32 v63, s61, v63
	v_mul_f32_e32 v64, s62, v64
	v_mul_f32_e32 v65, s62, v65
	v_mul_f32_e32 v66, s62, v66
	v_mul_f32_e32 v67, s62, v67
	v_mul_f32_e32 v68, s63, v68
	v_mul_f32_e32 v69, s63, v69
	v_mul_f32_e32 v70, s63, v70
	v_mul_f32_e32 v71, s63, v71
	s_mov_b64 exec, -1

.Lw1c_nog_16:
	s_bitcmp1_b32 s35, 1
	s_cselect_b64 vcc, -1, 0
	s_lshr_b32 s0, s35, 8
	s_lshl_b32 s4, 1, s0
	v_cndmask_b32_e32 v207, v202, v203, vcc
	v_lshlrev_b32_e32 v206, s0, v207
	v_add_u32_e32 v206, v206, v204
	s_waitcnt vmcnt(8)
	s_bitcmp1_b32 s35, 0
	s_cbranch_scc0 .Lw1c_nomul_16
	s_waitcnt lgkmcnt(0)
	s_mov_b32 exec_hi, 0
	v_mul_f32_e32 v72, s80, v72
	v_mul_f32_e32 v73, s80, v73
	v_mul_f32_e32 v74, s80, v74
	v_mul_f32_e32 v75, s80, v75
	v_mul_f32_e32 v76, s81, v76
	v_mul_f32_e32 v77, s81, v77
	v_mul_f32_e32 v78, s81, v78
	v_mul_f32_e32 v79, s81, v79
	v_mul_f32_e32 v80, s82, v80
	v_mul_f32_e32 v81, s82, v81
	v_mul_f32_e32 v82, s82, v82
	v_mul_f32_e32 v83, s82, v83
	v_mul_f32_e32 v84, s83, v84
	v_mul_f32_e32 v85, s83, v85
	v_mul_f32_e32 v86, s83, v86
	v_mul_f32_e32 v87, s83, v87
	v_mul_f32_e32 v88, s84, v88
	v_mul_f32_e32 v89, s84, v89
	v_mul_f32_e32 v90, s84, v90
	v_mul_f32_e32 v91, s84, v91
	v_mul_f32_e32 v92, s85, v92
	v_mul_f32_e32 v93, s85, v93
	v_mul_f32_e32 v94, s85, v94
	v_mul_f32_e32 v95, s85, v95
	v_mul_f32_e32 v96, s86, v96
	v_mul_f32_e32 v97, s86, v97
	v_mul_f32_e32 v98, s86, v98
	v_mul_f32_e32 v99, s86, v99
	v_mul_f32_e32 v100, s87, v100
	v_mul_f32_e32 v101, s87, v101
	v_mul_f32_e32 v102, s87, v102
	v_mul_f32_e32 v103, s87, v103
	v_mul_f32_e32 v104, s88, v104
	v_mul_f32_e32 v105, s88, v105
	v_mul_f32_e32 v106, s88, v106
	v_mul_f32_e32 v107, s88, v107
	v_mul_f32_e32 v108, s89, v108
	v_mul_f32_e32 v109, s89, v109
	v_mul_f32_e32 v110, s89, v110
	v_mul_f32_e32 v111, s89, v111
	v_mul_f32_e32 v112, s90, v112
	v_mul_f32_e32 v113, s90, v113
	v_mul_f32_e32 v114, s90, v114
	v_mul_f32_e32 v115, s90, v115
	v_mul_f32_e32 v116, s91, v116
	v_mul_f32_e32 v117, s91, v117
	v_mul_f32_e32 v118, s91, v118
	v_mul_f32_e32 v119, s91, v119
	v_mul_f32_e32 v120, s92, v120
	v_mul_f32_e32 v121, s92, v121
	v_mul_f32_e32 v122, s92, v122
	v_mul_f32_e32 v123, s92, v123
	v_mul_f32_e32 v124, s93, v124
	v_mul_f32_e32 v125, s93, v125
	v_mul_f32_e32 v126, s93, v126
	v_mul_f32_e32 v127, s93, v127
	v_mul_f32_e32 v128, s94, v128
	v_mul_f32_e32 v129, s94, v129
	v_mul_f32_e32 v130, s94, v130
	v_mul_f32_e32 v131, s94, v131
	v_mul_f32_e32 v132, s95, v132
	v_mul_f32_e32 v133, s95, v133
	v_mul_f32_e32 v134, s95, v134
	v_mul_f32_e32 v135, s95, v135
	s_mov_b32 exec_lo, 0
	s_mov_b32 exec_hi, -1
	v_mul_f32_e32 v72, s48, v72
	v_mul_f32_e32 v73, s48, v73
	v_mul_f32_e32 v74, s48, v74
	v_mul_f32_e32 v75, s48, v75
	v_mul_f32_e32 v76, s49, v76
	v_mul_f32_e32 v77, s49, v77
	v_mul_f32_e32 v78, s49, v78
	v_mul_f32_e32 v79, s49, v79
	v_mul_f32_e32 v80, s50, v80
	v_mul_f32_e32 v81, s50, v81
	v_mul_f32_e32 v82, s50, v82
	v_mul_f32_e32 v83, s50, v83
	v_mul_f32_e32 v84, s51, v84
	v_mul_f32_e32 v85, s51, v85
	v_mul_f32_e32 v86, s51, v86
	v_mul_f32_e32 v87, s51, v87
	v_mul_f32_e32 v88, s52, v88
	v_mul_f32_e32 v89, s52, v89
	v_mul_f32_e32 v90, s52, v90
	v_mul_f32_e32 v91, s52, v91
	v_mul_f32_e32 v92, s53, v92
	v_mul_f32_e32 v93, s53, v93
	v_mul_f32_e32 v94, s53, v94
	v_mul_f32_e32 v95, s53, v95
	v_mul_f32_e32 v96, s54, v96
	v_mul_f32_e32 v97, s54, v97
	v_mul_f32_e32 v98, s54, v98
	v_mul_f32_e32 v99, s54, v99
	v_mul_f32_e32 v100, s55, v100
	v_mul_f32_e32 v101, s55, v101
	v_mul_f32_e32 v102, s55, v102
	v_mul_f32_e32 v103, s55, v103
	v_mul_f32_e32 v104, s56, v104
	v_mul_f32_e32 v105, s56, v105
	v_mul_f32_e32 v106, s56, v106
	v_mul_f32_e32 v107, s56, v107
	v_mul_f32_e32 v108, s57, v108
	v_mul_f32_e32 v109, s57, v109
	v_mul_f32_e32 v110, s57, v110
	v_mul_f32_e32 v111, s57, v111
	v_mul_f32_e32 v112, s58, v112
	v_mul_f32_e32 v113, s58, v113
	v_mul_f32_e32 v114, s58, v114
	v_mul_f32_e32 v115, s58, v115
	v_mul_f32_e32 v116, s59, v116
	v_mul_f32_e32 v117, s59, v117
	v_mul_f32_e32 v118, s59, v118
	v_mul_f32_e32 v119, s59, v119
	v_mul_f32_e32 v120, s60, v120
	v_mul_f32_e32 v121, s60, v121
	v_mul_f32_e32 v122, s60, v122
	v_mul_f32_e32 v123, s60, v123
	v_mul_f32_e32 v124, s61, v124
	v_mul_f32_e32 v125, s61, v125
	v_mul_f32_e32 v126, s61, v126
	v_mul_f32_e32 v127, s61, v127
	v_mul_f32_e32 v128, s62, v128
	v_mul_f32_e32 v129, s62, v129
	v_mul_f32_e32 v130, s62, v130
	v_mul_f32_e32 v131, s62, v131
	v_mul_f32_e32 v132, s63, v132
	v_mul_f32_e32 v133, s63, v133
	v_mul_f32_e32 v134, s63, v134
	v_mul_f32_e32 v135, s63, v135
	s_mov_b64 exec, -1
.Lw1c_nomul_16:
	v_cvt_pk_bf16_f32 v236, v72, v76
	v_cvt_pk_bf16_f32 v237, v80, v84
	v_cvt_pk_bf16_f32 v238, v88, v92
	v_cvt_pk_bf16_f32 v239, v96, v100
	global_store_dwordx4 v206, v[236:239], s[30:31]
	v_cvt_pk_bf16_f32 v240, v104, v108
	v_cvt_pk_bf16_f32 v241, v112, v116
	v_cvt_pk_bf16_f32 v242, v120, v124
	v_cvt_pk_bf16_f32 v243, v128, v132
	global_store_dwordx4 v206, v[240:243], s[30:31] offset:16
	s_add_u32 s30, s30, s4
	s_addc_u32 s31, s31, 0
	v_cvt_pk_bf16_f32 v244, v73, v77
	v_cvt_pk_bf16_f32 v245, v81, v85
	v_cvt_pk_bf16_f32 v246, v89, v93
	v_cvt_pk_bf16_f32 v247, v97, v101
	global_store_dwordx4 v206, v[244:247], s[30:31]
	v_cvt_pk_bf16_f32 v248, v105, v109
	v_cvt_pk_bf16_f32 v249, v113, v117
	v_cvt_pk_bf16_f32 v250, v121, v125
	v_cvt_pk_bf16_f32 v251, v129, v133
	global_store_dwordx4 v206, v[248:251], s[30:31] offset:16
	s_add_u32 s30, s30, s4
	s_addc_u32 s31, s31, 0
	v_cvt_pk_bf16_f32 v236, v74, v78
	v_cvt_pk_bf16_f32 v237, v82, v86
	v_cvt_pk_bf16_f32 v238, v90, v94
	v_cvt_pk_bf16_f32 v239, v98, v102
	global_store_dwordx4 v206, v[236:239], s[30:31]
	v_cvt_pk_bf16_f32 v240, v106, v110
	v_cvt_pk_bf16_f32 v241, v114, v118
	v_cvt_pk_bf16_f32 v242, v122, v126
	v_cvt_pk_bf16_f32 v243, v130, v134
	global_store_dwordx4 v206, v[240:243], s[30:31] offset:16
	s_add_u32 s30, s30, s4
	s_addc_u32 s31, s31, 0
	v_cvt_pk_bf16_f32 v244, v75, v79
	v_cvt_pk_bf16_f32 v245, v83, v87
	v_cvt_pk_bf16_f32 v246, v91, v95
	v_cvt_pk_bf16_f32 v247, v99, v103
	global_store_dwordx4 v206, v[244:247], s[30:31]
	v_cvt_pk_bf16_f32 v248, v107, v111
	v_cvt_pk_bf16_f32 v249, v115, v119
	v_cvt_pk_bf16_f32 v250, v123, v127
	v_cvt_pk_bf16_f32 v251, v131, v135
	global_store_dwordx4 v206, v[248:251], s[30:31] offset:16
	v_readlane_b32 s8, v254, 0
	v_readlane_b32 s9, v254, 1
	v_readlane_b32 s10, v254, 2
	v_readlane_b32 s11, v254, 3
	v_readlane_b32 s12, v254, 4
	v_readlane_b32 s13, v254, 5
	v_readlane_b32 s14, v254, 6
	v_readlane_b32 s15, v254, 7
	v_readlane_b32 s16, v254, 8
	v_readlane_b32 s17, v254, 9
	v_readlane_b32 s18, v254, 10
	v_readlane_b32 s19, v254, 11
	v_readlane_b32 s20, v254, 12
	v_readlane_b32 s21, v254, 13
	v_readlane_b32 s22, v254, 14
	v_readlane_b32 s23, v254, 15
	v_readlane_b32 s24, v254, 16
	v_readlane_b32 s25, v254, 17
	v_readlane_b32 s26, v254, 18
	v_readlane_b32 s27, v254, 19
	v_readlane_b32 s28, v254, 20
	v_readlane_b32 s29, v254, 21
	v_readlane_b32 s30, v254, 22
	v_readlane_b32 s31, v254, 23
	v_readlane_b32 s32, v254, 24
	v_readlane_b32 s33, v254, 25
	v_readlane_b32 s34, v254, 26
	v_readlane_b32 s35, v254, 27
	v_readlane_b32 s40, v254, 28
	v_readlane_b32 s41, v254, 29
	v_readlane_b32 s42, v254, 30
	v_readlane_b32 s43, v254, 31
	v_readlane_b32 s44, v254, 32
	v_readlane_b32 s45, v254, 33
	v_readlane_b32 s46, v254, 34
	v_readlane_b32 s47, v254, 35
	v_readlane_b32 s48, v254, 36
	v_readlane_b32 s49, v254, 37
	v_readlane_b32 s50, v254, 38
	v_readlane_b32 s51, v254, 39
	v_readlane_b32 s52, v254, 40
	v_readlane_b32 s53, v254, 41
	v_readlane_b32 s54, v254, 42
	v_readlane_b32 s55, v254, 43
	v_readlane_b32 s56, v254, 44
	v_readlane_b32 s57, v254, 45
	v_readlane_b32 s58, v254, 46
	v_readlane_b32 s59, v254, 47
	v_readlane_b32 s60, v254, 48
	v_readlane_b32 s61, v254, 49
	v_readlane_b32 s62, v254, 50
	v_readlane_b32 s63, v254, 51
	v_readlane_b32 s66, v254, 52
	v_readlane_b32 s67, v254, 53
	v_readlane_b32 s68, v254, 54
	v_readlane_b32 s69, v254, 55
	v_readlane_b32 s70, v254, 56
	v_readlane_b32 s71, v254, 57
	v_readlane_b32 s72, v254, 58
	v_readlane_b32 s73, v254, 59
	v_readlane_b32 s74, v254, 60
	v_readlane_b32 s75, v254, 61
	v_readlane_b32 s76, v254, 62
	v_readlane_b32 s77, v254, 63
	v_readlane_b32 s80, v255, 0
	v_readlane_b32 s81, v255, 1
	v_readlane_b32 s82, v255, 2
	v_readlane_b32 s83, v255, 3
	v_readlane_b32 s84, v255, 4
	v_readlane_b32 s85, v255, 5
	v_readlane_b32 s86, v255, 6
	v_readlane_b32 s87, v255, 7
	v_readlane_b32 s88, v255, 8
	v_readlane_b32 s89, v255, 9
	v_readlane_b32 s90, v255, 10
	v_readlane_b32 s91, v255, 11
	v_readlane_b32 s92, v255, 12
	v_readlane_b32 s93, v255, 13
	v_readlane_b32 s94, v255, 14
	v_readlane_b32 s95, v255, 15
	v_readlane_b32 s4, v255, 16
	v_readlane_b32 s5, v255, 17
	v_readlane_b32 s0, v255, 18
	v_readlane_b32 s1, v255, 19
